# scan phase: both column iterations in flight (62 loads up front, SGPR base + VGPR chunk offsets, two interleaved scan chains, decay computed once)
# baseline (speedup 1.0000x reference)
.LBB0_567:
	s_or_b64 exec, exec, s[0:1]
	s_add_u32 s30, s50, 0x3a00000
	v_lshl_add_u32 v64, s2, 8, v131
	s_mov_b32 s6, 0x40000
	s_addc_u32 s31, s51, 0
	v_cmp_gt_i32_e32 vcc, s6, v64
	s_waitcnt lgkmcnt(0)
	s_barrier
	s_and_saveexec_b64 s[0:1], vcc
	s_cbranch_execz .LBB0_570
	s_lshl_b32 s7, s3, 8
	s_mov_b64 s[4:5], 0
	s_mov_b32 s8, 0xc2fc0000
	v_mov_b32_e32 v65, 0x42800000
	v_mov_b32_e32 v1, 0
	v_not_b32_e32 v66, 63
	s_mov_b32 s9, 0x3f2aaaab
	v_mov_b32_e32 v67, 0x3ecc95a3
	s_mov_b32 s10, 0x3f317218
	v_mov_b32_e32 v68, 0x7fc00000
	v_mov_b32_e32 v69, 0xff800000
	s_mov_b32 s11, 0x33800000
	s_mov_b32 s12, 0x8000
	s_mov_b32 s13, 0x10000
	s_mov_b32 s14, 0x18000
	s_mov_b32 s15, 0x20000
	s_mov_b32 s18, 0x28000
	s_mov_b32 s19, 0x30000
	s_mov_b32 s20, 0x38000
	s_mov_b32 s21, 0x48000
	s_mov_b32 s22, 0x50000
	s_mov_b32 s23, 0x58000
	s_mov_b32 s24, 0x60000
	s_mov_b32 s25, 0x68000
	s_mov_b32 s26, 0x70000
	s_mov_b32 s27, 0x78000
	s_mov_b32 s28, 0x80000
	s_mov_b32 s29, 0x88000
	s_mov_b32 s33, 0x90000
	s_mov_b32 s34, 0x98000
	s_mov_b32 s35, 0xa0000
	s_mov_b32 s38, 0xa8000
	s_mov_b32 s39, 0xb0000
	s_mov_b32 s40, 0xb8000
	s_mov_b32 s41, 0xc0000
	s_mov_b32 s42, 0xc8000
	s_mov_b32 s43, 0xd0000
	s_mov_b32 s44, 0xd8000
	s_mov_b32 s45, 0xe0000
	s_mov_b32 s46, 0xe8000
	s_mov_b32 s47, 0xf0000
	s_mov_b32 s52, 0xffff0000
	s_movk_i32 s53, 0x7fff
	s_mov_b32 s54, 0x3ffff
	s_cmp_lg_u32 s3, 0x200
	s_cbranch_scc1 .LBB0_569
	s_lshr_b32 s4, s2, 5
	s_lshl_b32 s4, s4, 20
	s_add_u32 s4, s30, s4
	s_addc_u32 s5, s31, 0
	s_add_u32 s6, s4, 0x1000000
	s_addc_u32 s7, s5, 0
	v_and_b32_e32 v6, 0x1fff, v64
	v_lshlrev_b32_e32 v6, 2, v6
	global_load_dword v73, v6, s[4:5]
	global_load_dword v38, v6, s[6:7]
	v_add_u32_e32 v7, 0x8000, v6
	global_load_dword v74, v7, s[4:5]
	global_load_dword v39, v7, s[6:7]
	v_add_u32_e32 v8, 0x10000, v6
	global_load_dword v75, v8, s[4:5]
	global_load_dword v40, v8, s[6:7]
	v_add_u32_e32 v9, 0x18000, v6
	global_load_dword v76, v9, s[4:5]
	global_load_dword v41, v9, s[6:7]
	v_add_u32_e32 v10, 0x20000, v6
	global_load_dword v77, v10, s[4:5]
	global_load_dword v42, v10, s[6:7]
	v_add_u32_e32 v11, 0x28000, v6
	global_load_dword v78, v11, s[4:5]
	global_load_dword v43, v11, s[6:7]
	v_add_u32_e32 v12, 0x30000, v6
	global_load_dword v79, v12, s[4:5]
	global_load_dword v44, v12, s[6:7]
	v_add_u32_e32 v13, 0x38000, v6
	global_load_dword v80, v13, s[4:5]
	global_load_dword v45, v13, s[6:7]
	v_add_u32_e32 v14, 0x40000, v6
	global_load_dword v81, v14, s[4:5]
	global_load_dword v46, v14, s[6:7]
	v_add_u32_e32 v15, 0x48000, v6
	global_load_dword v82, v15, s[4:5]
	global_load_dword v47, v15, s[6:7]
	v_add_u32_e32 v16, 0x50000, v6
	global_load_dword v83, v16, s[4:5]
	global_load_dword v48, v16, s[6:7]
	v_add_u32_e32 v17, 0x58000, v6
	global_load_dword v84, v17, s[4:5]
	global_load_dword v49, v17, s[6:7]
	v_add_u32_e32 v18, 0x60000, v6
	global_load_dword v85, v18, s[4:5]
	global_load_dword v50, v18, s[6:7]
	v_add_u32_e32 v19, 0x68000, v6
	global_load_dword v86, v19, s[4:5]
	global_load_dword v51, v19, s[6:7]
	v_add_u32_e32 v20, 0x70000, v6
	global_load_dword v87, v20, s[4:5]
	global_load_dword v52, v20, s[6:7]
	v_add_u32_e32 v21, 0x78000, v6
	global_load_dword v88, v21, s[4:5]
	global_load_dword v53, v21, s[6:7]
	v_add_u32_e32 v22, 0x80000, v6
	global_load_dword v89, v22, s[4:5]
	global_load_dword v54, v22, s[6:7]
	v_add_u32_e32 v23, 0x88000, v6
	global_load_dword v90, v23, s[4:5]
	global_load_dword v55, v23, s[6:7]
	v_add_u32_e32 v24, 0x90000, v6
	global_load_dword v91, v24, s[4:5]
	global_load_dword v56, v24, s[6:7]
	v_add_u32_e32 v25, 0x98000, v6
	global_load_dword v92, v25, s[4:5]
	global_load_dword v57, v25, s[6:7]
	v_add_u32_e32 v26, 0xa0000, v6
	global_load_dword v93, v26, s[4:5]
	global_load_dword v58, v26, s[6:7]
	v_add_u32_e32 v27, 0xa8000, v6
	global_load_dword v94, v27, s[4:5]
	global_load_dword v59, v27, s[6:7]
	v_add_u32_e32 v28, 0xb0000, v6
	global_load_dword v95, v28, s[4:5]
	global_load_dword v60, v28, s[6:7]
	v_add_u32_e32 v29, 0xb8000, v6
	global_load_dword v96, v29, s[4:5]
	global_load_dword v61, v29, s[6:7]
	v_add_u32_e32 v30, 0xc0000, v6
	global_load_dword v97, v30, s[4:5]
	global_load_dword v62, v30, s[6:7]
	v_add_u32_e32 v31, 0xc8000, v6
	global_load_dword v98, v31, s[4:5]
	global_load_dword v63, v31, s[6:7]
	v_add_u32_e32 v32, 0xd0000, v6
	global_load_dword v99, v32, s[4:5]
	global_load_dword v113, v32, s[6:7]
	v_add_u32_e32 v33, 0xd8000, v6
	global_load_dword v100, v33, s[4:5]
	global_load_dword v114, v33, s[6:7]
	v_add_u32_e32 v34, 0xe0000, v6
	global_load_dword v101, v34, s[4:5]
	global_load_dword v115, v34, s[6:7]
	v_add_u32_e32 v35, 0xe8000, v6
	global_load_dword v102, v35, s[4:5]
	global_load_dword v116, v35, s[6:7]
	v_add_u32_e32 v36, 0xf0000, v6
	global_load_dword v103, v36, s[4:5]
	global_load_dword v117, v36, s[6:7]
	v_add_u32_e32 v37, 0xf8000, v6
	v_ashrrev_i32_e32 v2, 13, v64
	v_and_b32_e32 v4, 7, v2
	v_cvt_f32_ubyte0_e32 v4, v4
	v_sub_f32_e32 v4, 0xc0a00000, v4
	v_cmp_gt_f32_e32 vcc, s8, v4
	s_nop 1
	v_cndmask_b32_e32 v5, 0, v65, vcc
	v_cndmask_b32_e32 v72, 0, v66, vcc
	v_add_f32_e32 v0, v4, v5
	v_exp_f32_e32 v0, v0
	s_nop 1
	v_ldexp_f32 v0, v0, v72
	v_sub_f32_e32 v72, 1.0, v0
	v_add_f32_e32 v104, -1.0, v72
	v_frexp_mant_f32_e32 v105, v72
	v_sub_f32_e32 v106, v104, v72
	v_sub_f32_e64 v104, -v0, v104
	v_cvt_f64_f32_e32 v[70:71], v72
	v_frexp_exp_i32_f64_e32 v70, v[70:71]
	v_cmp_gt_f32_e32 vcc, s9, v105
	v_add_f32_e32 v71, 1.0, v106
	v_add_f32_e32 v71, v104, v71
	v_subbrev_co_u32_e32 v70, vcc, 0, v70, vcc
	v_sub_u32_e32 v104, 0, v70
	v_cvt_f32_i32_e32 v70, v70
	v_ldexp_f32 v72, v72, v104
	v_ldexp_f32 v71, v71, v104
	v_add_f32_e32 v104, -1.0, v72
	v_add_f32_e32 v105, 1.0, v72
	v_add_f32_e32 v106, 1.0, v104
	v_add_f32_e32 v107, -1.0, v105
	v_sub_f32_e32 v106, v72, v106
	v_sub_f32_e32 v72, v72, v107
	v_mul_f32_e32 v107, 0x3f317218, v70
	v_add_f32_e32 v106, v71, v106
	v_add_f32_e32 v71, v71, v72
	v_fma_f32 v72, v70, s10, -v107
	v_add_f32_e32 v108, v104, v106
	v_add_f32_e32 v109, v105, v71
	v_fmac_f32_e32 v72, 0xb102e308, v70
	v_sub_f32_e32 v70, v108, v104
	v_sub_f32_e32 v104, v109, v105
	v_rcp_f32_e32 v105, v109
	v_add_f32_e32 v110, v107, v72
	v_sub_f32_e32 v71, v71, v104
	v_sub_f32_e32 v104, v110, v107
	v_sub_f32_e32 v72, v72, v104
	v_mul_f32_e32 v104, v108, v105
	v_sub_f32_e32 v70, v106, v70
	v_mul_f32_e32 v106, v109, v104
	v_fma_f32 v107, v104, v109, -v106
	v_fmac_f32_e32 v107, v104, v71
	v_add_f32_e32 v111, v106, v107
	v_sub_f32_e32 v112, v108, v111
	v_sub_f32_e32 v106, v111, v106
	v_sub_f32_e32 v108, v108, v112
	v_sub_f32_e32 v106, v106, v107
	v_sub_f32_e32 v107, v108, v111
	v_add_f32_e32 v70, v70, v107
	v_add_f32_e32 v70, v106, v70
	v_add_f32_e32 v106, v112, v70
	v_mul_f32_e32 v107, v105, v106
	v_sub_f32_e32 v108, v112, v106
	v_mul_f32_e32 v111, v109, v107
	v_add_f32_e32 v70, v70, v108
	v_add_f32_e32 v108, v104, v107
	v_fma_f32 v109, v107, v109, -v111
	v_sub_f32_e32 v104, v108, v104
	v_fmac_f32_e32 v109, v107, v71
	v_sub_f32_e32 v71, v107, v104
	v_add_f32_e32 v104, v111, v109
	v_sub_f32_e32 v107, v104, v111
	v_sub_f32_e32 v111, v106, v104
	v_sub_f32_e32 v106, v106, v111
	v_sub_f32_e32 v104, v106, v104
	v_sub_f32_e32 v107, v107, v109
	v_add_f32_e32 v70, v70, v104
	v_add_f32_e32 v70, v107, v70
	v_add_f32_e32 v70, v111, v70
	v_mul_f32_e32 v70, v105, v70
	v_add_f32_e32 v70, v71, v70
	v_add_f32_e32 v71, v108, v70
	v_mul_f32_e32 v104, v71, v71
	v_fmamk_f32 v107, v104, 0x3e9b6dac, v67
	v_sub_f32_e32 v105, v71, v108
	v_ldexp_f32 v106, v71, 1
	v_mul_f32_e32 v71, v71, v104
	v_fmaak_f32 v104, v104, v107, 0x3f2aaada
	v_mul_f32_e32 v71, v71, v104
	v_add_f32_e32 v104, v106, v71
	v_sub_f32_e32 v70, v70, v105
	v_sub_f32_e32 v105, v104, v106
	v_ldexp_f32 v70, v70, 1
	v_sub_f32_e32 v71, v71, v105
	v_add_f32_e32 v70, v70, v71
	v_add_f32_e32 v71, v104, v70
	v_sub_f32_e32 v104, v71, v104
	v_add_f32_e32 v105, v110, v71
	v_sub_f32_e32 v70, v70, v104
	v_sub_f32_e32 v104, v105, v110
	v_sub_f32_e32 v106, v105, v104
	v_sub_f32_e32 v71, v71, v104
	v_add_f32_e32 v104, v72, v70
	v_sub_f32_e32 v106, v110, v106
	v_sub_f32_e32 v107, v104, v72
	v_add_f32_e32 v71, v71, v106
	v_sub_f32_e32 v106, v104, v107
	v_sub_f32_e32 v70, v70, v107
	v_sub_f32_e32 v72, v72, v106
	v_add_f32_e32 v71, v104, v71
	v_add_f32_e32 v70, v70, v72
	v_add_f32_e32 v72, v105, v71
	v_sub_f32_e32 v104, v72, v105
	v_sub_f32_e32 v71, v71, v104
	v_add_f32_e32 v70, v70, v71
	v_add_f32_e32 v70, v72, v70
	v_cmp_nlt_f32_e32 vcc, 1.0, v0
	s_nop 1
	v_cndmask_b32_e32 v70, v68, v70, vcc
	v_cmp_neq_f32_e32 vcc, 1.0, v0
	s_nop 1
	v_cndmask_b32_e32 v70, v69, v70, vcc
	v_cmp_gt_f32_e32 vcc, s11, v0
	s_nop 1
	v_cndmask_b32_e64 v0, v70, -v0, vcc
	v_mul_f32_e32 v0, 0x43000000, v0
	v_mul_f32_e32 v0, 0x3fb8aa3b, v0
	v_exp_f32_e32 v0, v0
	s_nop 1
	s_waitcnt vmcnt(61)
	s_waitcnt vmcnt(60)
	v_lshlrev_b32_e32 v118, 16, v73
	v_lshlrev_b32_e32 v126, 16, v38
	v_and_b32_e32 v73, 0xffff0000, v73
	v_and_b32_e32 v38, 0xffff0000, v38
	v_fmac_f32_e32 v118, 0, v0
	v_fmac_f32_e32 v126, 0, v0
	v_fmac_f32_e32 v73, 0, v0
	v_fmac_f32_e32 v38, 0, v0
	v_bfe_u32 v120, v118, 16, 1
	v_bfe_u32 v140, v126, 16, 1
	v_bfe_u32 v124, v73, 16, 1
	v_bfe_u32 v144, v38, 16, 1
	v_add3_u32 v120, v118, v120, s53
	v_add3_u32 v140, v126, v140, s53
	v_add3_u32 v124, v73, v124, s53
	v_add3_u32 v144, v38, v144, s53
	v_lshrrev_b32_e32 v120, 16, v120
	v_lshrrev_b32_e32 v140, 16, v140
	v_and_or_b32 v120, v124, s52, v120
	v_and_or_b32 v140, v144, s52, v140
	global_store_dword v7, v120, s[4:5]
	global_store_dword v7, v140, s[6:7]
	global_store_dword v6, v1, s[4:5]
	global_store_dword v6, v1, s[6:7]
	s_waitcnt vmcnt(63)
	s_waitcnt vmcnt(62)
	v_lshlrev_b32_e32 v119, 16, v74
	v_lshlrev_b32_e32 v127, 16, v39
	v_and_b32_e32 v74, 0xffff0000, v74
	v_and_b32_e32 v39, 0xffff0000, v39
	v_fmac_f32_e32 v119, v0, v118
	v_fmac_f32_e32 v127, v0, v126
	v_fmac_f32_e32 v74, v0, v73
	v_fmac_f32_e32 v39, v0, v38
	v_bfe_u32 v121, v119, 16, 1
	v_bfe_u32 v141, v127, 16, 1
	v_bfe_u32 v125, v74, 16, 1
	v_bfe_u32 v145, v39, 16, 1
	v_add3_u32 v121, v119, v121, s53
	v_add3_u32 v141, v127, v141, s53
	v_add3_u32 v125, v74, v125, s53
	v_add3_u32 v145, v39, v145, s53
	v_lshrrev_b32_e32 v121, 16, v121
	v_lshrrev_b32_e32 v141, 16, v141
	v_and_or_b32 v121, v125, s52, v121
	v_and_or_b32 v141, v145, s52, v141
	global_store_dword v8, v121, s[4:5]
	global_store_dword v8, v141, s[6:7]
	s_waitcnt vmcnt(63)
	s_waitcnt vmcnt(62)
	v_lshlrev_b32_e32 v118, 16, v75
	v_lshlrev_b32_e32 v126, 16, v40
	v_and_b32_e32 v75, 0xffff0000, v75
	v_and_b32_e32 v40, 0xffff0000, v40
	v_fmac_f32_e32 v118, v0, v119
	v_fmac_f32_e32 v126, v0, v127
	v_fmac_f32_e32 v75, v0, v74
	v_fmac_f32_e32 v40, v0, v39
	v_bfe_u32 v122, v118, 16, 1
	v_bfe_u32 v142, v126, 16, 1
	v_bfe_u32 v124, v75, 16, 1
	v_bfe_u32 v144, v40, 16, 1
	v_add3_u32 v122, v118, v122, s53
	v_add3_u32 v142, v126, v142, s53
	v_add3_u32 v124, v75, v124, s53
	v_add3_u32 v144, v40, v144, s53
	v_lshrrev_b32_e32 v122, 16, v122
	v_lshrrev_b32_e32 v142, 16, v142
	v_and_or_b32 v122, v124, s52, v122
	v_and_or_b32 v142, v144, s52, v142
	global_store_dword v9, v122, s[4:5]
	global_store_dword v9, v142, s[6:7]
	s_waitcnt vmcnt(63)
	s_waitcnt vmcnt(62)
	v_lshlrev_b32_e32 v119, 16, v76
	v_lshlrev_b32_e32 v127, 16, v41
	v_and_b32_e32 v76, 0xffff0000, v76
	v_and_b32_e32 v41, 0xffff0000, v41
	v_fmac_f32_e32 v119, v0, v118
	v_fmac_f32_e32 v127, v0, v126
	v_fmac_f32_e32 v76, v0, v75
	v_fmac_f32_e32 v41, v0, v40
	v_bfe_u32 v123, v119, 16, 1
	v_bfe_u32 v143, v127, 16, 1
	v_bfe_u32 v125, v76, 16, 1
	v_bfe_u32 v145, v41, 16, 1
	v_add3_u32 v123, v119, v123, s53
	v_add3_u32 v143, v127, v143, s53
	v_add3_u32 v125, v76, v125, s53
	v_add3_u32 v145, v41, v145, s53
	v_lshrrev_b32_e32 v123, 16, v123
	v_lshrrev_b32_e32 v143, 16, v143
	v_and_or_b32 v123, v125, s52, v123
	v_and_or_b32 v143, v145, s52, v143
	global_store_dword v10, v123, s[4:5]
	global_store_dword v10, v143, s[6:7]
	s_waitcnt vmcnt(63)
	s_waitcnt vmcnt(62)
	v_lshlrev_b32_e32 v118, 16, v77
	v_lshlrev_b32_e32 v126, 16, v42
	v_and_b32_e32 v77, 0xffff0000, v77
	v_and_b32_e32 v42, 0xffff0000, v42
	v_fmac_f32_e32 v118, v0, v119
	v_fmac_f32_e32 v126, v0, v127
	v_fmac_f32_e32 v77, v0, v76
	v_fmac_f32_e32 v42, v0, v41
	v_bfe_u32 v120, v118, 16, 1
	v_bfe_u32 v140, v126, 16, 1
	v_bfe_u32 v124, v77, 16, 1
	v_bfe_u32 v144, v42, 16, 1
	v_add3_u32 v120, v118, v120, s53
	v_add3_u32 v140, v126, v140, s53
	v_add3_u32 v124, v77, v124, s53
	v_add3_u32 v144, v42, v144, s53
	v_lshrrev_b32_e32 v120, 16, v120
	v_lshrrev_b32_e32 v140, 16, v140
	v_and_or_b32 v120, v124, s52, v120
	v_and_or_b32 v140, v144, s52, v140
	global_store_dword v11, v120, s[4:5]
	global_store_dword v11, v140, s[6:7]
	s_waitcnt vmcnt(63)
	s_waitcnt vmcnt(62)
	v_lshlrev_b32_e32 v119, 16, v78
	v_lshlrev_b32_e32 v127, 16, v43
	v_and_b32_e32 v78, 0xffff0000, v78
	v_and_b32_e32 v43, 0xffff0000, v43
	v_fmac_f32_e32 v119, v0, v118
	v_fmac_f32_e32 v127, v0, v126
	v_fmac_f32_e32 v78, v0, v77
	v_fmac_f32_e32 v43, v0, v42
	v_bfe_u32 v121, v119, 16, 1
	v_bfe_u32 v141, v127, 16, 1
	v_bfe_u32 v125, v78, 16, 1
	v_bfe_u32 v145, v43, 16, 1
	v_add3_u32 v121, v119, v121, s53
	v_add3_u32 v141, v127, v141, s53
	v_add3_u32 v125, v78, v125, s53
	v_add3_u32 v145, v43, v145, s53
	v_lshrrev_b32_e32 v121, 16, v121
	v_lshrrev_b32_e32 v141, 16, v141
	v_and_or_b32 v121, v125, s52, v121
	v_and_or_b32 v141, v145, s52, v141
	global_store_dword v12, v121, s[4:5]
	global_store_dword v12, v141, s[6:7]
	s_waitcnt vmcnt(63)
	s_waitcnt vmcnt(62)
	v_lshlrev_b32_e32 v118, 16, v79
	v_lshlrev_b32_e32 v126, 16, v44
	v_and_b32_e32 v79, 0xffff0000, v79
	v_and_b32_e32 v44, 0xffff0000, v44
	v_fmac_f32_e32 v118, v0, v119
	v_fmac_f32_e32 v126, v0, v127
	v_fmac_f32_e32 v79, v0, v78
	v_fmac_f32_e32 v44, v0, v43
	v_bfe_u32 v122, v118, 16, 1
	v_bfe_u32 v142, v126, 16, 1
	v_bfe_u32 v124, v79, 16, 1
	v_bfe_u32 v144, v44, 16, 1
	v_add3_u32 v122, v118, v122, s53
	v_add3_u32 v142, v126, v142, s53
	v_add3_u32 v124, v79, v124, s53
	v_add3_u32 v144, v44, v144, s53
	v_lshrrev_b32_e32 v122, 16, v122
	v_lshrrev_b32_e32 v142, 16, v142
	v_and_or_b32 v122, v124, s52, v122
	v_and_or_b32 v142, v144, s52, v142
	global_store_dword v13, v122, s[4:5]
	global_store_dword v13, v142, s[6:7]
	s_waitcnt vmcnt(63)
	s_waitcnt vmcnt(62)
	v_lshlrev_b32_e32 v119, 16, v80
	v_lshlrev_b32_e32 v127, 16, v45
	v_and_b32_e32 v80, 0xffff0000, v80
	v_and_b32_e32 v45, 0xffff0000, v45
	v_fmac_f32_e32 v119, v0, v118
	v_fmac_f32_e32 v127, v0, v126
	v_fmac_f32_e32 v80, v0, v79
	v_fmac_f32_e32 v45, v0, v44
	v_bfe_u32 v123, v119, 16, 1
	v_bfe_u32 v143, v127, 16, 1
	v_bfe_u32 v125, v80, 16, 1
	v_bfe_u32 v145, v45, 16, 1
	v_add3_u32 v123, v119, v123, s53
	v_add3_u32 v143, v127, v143, s53
	v_add3_u32 v125, v80, v125, s53
	v_add3_u32 v145, v45, v145, s53
	v_lshrrev_b32_e32 v123, 16, v123
	v_lshrrev_b32_e32 v143, 16, v143
	v_and_or_b32 v123, v125, s52, v123
	v_and_or_b32 v143, v145, s52, v143
	global_store_dword v14, v123, s[4:5]
	global_store_dword v14, v143, s[6:7]
	s_waitcnt vmcnt(63)
	s_waitcnt vmcnt(62)
	v_lshlrev_b32_e32 v118, 16, v81
	v_lshlrev_b32_e32 v126, 16, v46
	v_and_b32_e32 v81, 0xffff0000, v81
	v_and_b32_e32 v46, 0xffff0000, v46
	v_fmac_f32_e32 v118, v0, v119
	v_fmac_f32_e32 v126, v0, v127
	v_fmac_f32_e32 v81, v0, v80
	v_fmac_f32_e32 v46, v0, v45
	v_bfe_u32 v120, v118, 16, 1
	v_bfe_u32 v140, v126, 16, 1
	v_bfe_u32 v124, v81, 16, 1
	v_bfe_u32 v144, v46, 16, 1
	v_add3_u32 v120, v118, v120, s53
	v_add3_u32 v140, v126, v140, s53
	v_add3_u32 v124, v81, v124, s53
	v_add3_u32 v144, v46, v144, s53
	v_lshrrev_b32_e32 v120, 16, v120
	v_lshrrev_b32_e32 v140, 16, v140
	v_and_or_b32 v120, v124, s52, v120
	v_and_or_b32 v140, v144, s52, v140
	global_store_dword v15, v120, s[4:5]
	global_store_dword v15, v140, s[6:7]
	s_waitcnt vmcnt(63)
	s_waitcnt vmcnt(62)
	v_lshlrev_b32_e32 v119, 16, v82
	v_lshlrev_b32_e32 v127, 16, v47
	v_and_b32_e32 v82, 0xffff0000, v82
	v_and_b32_e32 v47, 0xffff0000, v47
	v_fmac_f32_e32 v119, v0, v118
	v_fmac_f32_e32 v127, v0, v126
	v_fmac_f32_e32 v82, v0, v81
	v_fmac_f32_e32 v47, v0, v46
	v_bfe_u32 v121, v119, 16, 1
	v_bfe_u32 v141, v127, 16, 1
	v_bfe_u32 v125, v82, 16, 1
	v_bfe_u32 v145, v47, 16, 1
	v_add3_u32 v121, v119, v121, s53
	v_add3_u32 v141, v127, v141, s53
	v_add3_u32 v125, v82, v125, s53
	v_add3_u32 v145, v47, v145, s53
	v_lshrrev_b32_e32 v121, 16, v121
	v_lshrrev_b32_e32 v141, 16, v141
	v_and_or_b32 v121, v125, s52, v121
	v_and_or_b32 v141, v145, s52, v141
	global_store_dword v16, v121, s[4:5]
	global_store_dword v16, v141, s[6:7]
	s_waitcnt vmcnt(63)
	s_waitcnt vmcnt(62)
	v_lshlrev_b32_e32 v118, 16, v83
	v_lshlrev_b32_e32 v126, 16, v48
	v_and_b32_e32 v83, 0xffff0000, v83
	v_and_b32_e32 v48, 0xffff0000, v48
	v_fmac_f32_e32 v118, v0, v119
	v_fmac_f32_e32 v126, v0, v127
	v_fmac_f32_e32 v83, v0, v82
	v_fmac_f32_e32 v48, v0, v47
	v_bfe_u32 v122, v118, 16, 1
	v_bfe_u32 v142, v126, 16, 1
	v_bfe_u32 v124, v83, 16, 1
	v_bfe_u32 v144, v48, 16, 1
	v_add3_u32 v122, v118, v122, s53
	v_add3_u32 v142, v126, v142, s53
	v_add3_u32 v124, v83, v124, s53
	v_add3_u32 v144, v48, v144, s53
	v_lshrrev_b32_e32 v122, 16, v122
	v_lshrrev_b32_e32 v142, 16, v142
	v_and_or_b32 v122, v124, s52, v122
	v_and_or_b32 v142, v144, s52, v142
	global_store_dword v17, v122, s[4:5]
	global_store_dword v17, v142, s[6:7]
	s_waitcnt vmcnt(63)
	s_waitcnt vmcnt(62)
	v_lshlrev_b32_e32 v119, 16, v84
	v_lshlrev_b32_e32 v127, 16, v49
	v_and_b32_e32 v84, 0xffff0000, v84
	v_and_b32_e32 v49, 0xffff0000, v49
	v_fmac_f32_e32 v119, v0, v118
	v_fmac_f32_e32 v127, v0, v126
	v_fmac_f32_e32 v84, v0, v83
	v_fmac_f32_e32 v49, v0, v48
	v_bfe_u32 v123, v119, 16, 1
	v_bfe_u32 v143, v127, 16, 1
	v_bfe_u32 v125, v84, 16, 1
	v_bfe_u32 v145, v49, 16, 1
	v_add3_u32 v123, v119, v123, s53
	v_add3_u32 v143, v127, v143, s53
	v_add3_u32 v125, v84, v125, s53
	v_add3_u32 v145, v49, v145, s53
	v_lshrrev_b32_e32 v123, 16, v123
	v_lshrrev_b32_e32 v143, 16, v143
	v_and_or_b32 v123, v125, s52, v123
	v_and_or_b32 v143, v145, s52, v143
	global_store_dword v18, v123, s[4:5]
	global_store_dword v18, v143, s[6:7]
	s_waitcnt vmcnt(63)
	s_waitcnt vmcnt(62)
	v_lshlrev_b32_e32 v118, 16, v85
	v_lshlrev_b32_e32 v126, 16, v50
	v_and_b32_e32 v85, 0xffff0000, v85
	v_and_b32_e32 v50, 0xffff0000, v50
	v_fmac_f32_e32 v118, v0, v119
	v_fmac_f32_e32 v126, v0, v127
	v_fmac_f32_e32 v85, v0, v84
	v_fmac_f32_e32 v50, v0, v49
	v_bfe_u32 v120, v118, 16, 1
	v_bfe_u32 v140, v126, 16, 1
	v_bfe_u32 v124, v85, 16, 1
	v_bfe_u32 v144, v50, 16, 1
	v_add3_u32 v120, v118, v120, s53
	v_add3_u32 v140, v126, v140, s53
	v_add3_u32 v124, v85, v124, s53
	v_add3_u32 v144, v50, v144, s53
	v_lshrrev_b32_e32 v120, 16, v120
	v_lshrrev_b32_e32 v140, 16, v140
	v_and_or_b32 v120, v124, s52, v120
	v_and_or_b32 v140, v144, s52, v140
	global_store_dword v19, v120, s[4:5]
	global_store_dword v19, v140, s[6:7]
	s_waitcnt vmcnt(63)
	s_waitcnt vmcnt(62)
	v_lshlrev_b32_e32 v119, 16, v86
	v_lshlrev_b32_e32 v127, 16, v51
	v_and_b32_e32 v86, 0xffff0000, v86
	v_and_b32_e32 v51, 0xffff0000, v51
	v_fmac_f32_e32 v119, v0, v118
	v_fmac_f32_e32 v127, v0, v126
	v_fmac_f32_e32 v86, v0, v85
	v_fmac_f32_e32 v51, v0, v50
	v_bfe_u32 v121, v119, 16, 1
	v_bfe_u32 v141, v127, 16, 1
	v_bfe_u32 v125, v86, 16, 1
	v_bfe_u32 v145, v51, 16, 1
	v_add3_u32 v121, v119, v121, s53
	v_add3_u32 v141, v127, v141, s53
	v_add3_u32 v125, v86, v125, s53
	v_add3_u32 v145, v51, v145, s53
	v_lshrrev_b32_e32 v121, 16, v121
	v_lshrrev_b32_e32 v141, 16, v141
	v_and_or_b32 v121, v125, s52, v121
	v_and_or_b32 v141, v145, s52, v141
	global_store_dword v20, v121, s[4:5]
	global_store_dword v20, v141, s[6:7]
	s_waitcnt vmcnt(63)
	s_waitcnt vmcnt(62)
	v_lshlrev_b32_e32 v118, 16, v87
	v_lshlrev_b32_e32 v126, 16, v52
	v_and_b32_e32 v87, 0xffff0000, v87
	v_and_b32_e32 v52, 0xffff0000, v52
	v_fmac_f32_e32 v118, v0, v119
	v_fmac_f32_e32 v126, v0, v127
	v_fmac_f32_e32 v87, v0, v86
	v_fmac_f32_e32 v52, v0, v51
	v_bfe_u32 v122, v118, 16, 1
	v_bfe_u32 v142, v126, 16, 1
	v_bfe_u32 v124, v87, 16, 1
	v_bfe_u32 v144, v52, 16, 1
	v_add3_u32 v122, v118, v122, s53
	v_add3_u32 v142, v126, v142, s53
	v_add3_u32 v124, v87, v124, s53
	v_add3_u32 v144, v52, v144, s53
	v_lshrrev_b32_e32 v122, 16, v122
	v_lshrrev_b32_e32 v142, 16, v142
	v_and_or_b32 v122, v124, s52, v122
	v_and_or_b32 v142, v144, s52, v142
	global_store_dword v21, v122, s[4:5]
	global_store_dword v21, v142, s[6:7]
	s_waitcnt vmcnt(63)
	s_waitcnt vmcnt(62)
	v_lshlrev_b32_e32 v119, 16, v88
	v_lshlrev_b32_e32 v127, 16, v53
	v_and_b32_e32 v88, 0xffff0000, v88
	v_and_b32_e32 v53, 0xffff0000, v53
	v_fmac_f32_e32 v119, v0, v118
	v_fmac_f32_e32 v127, v0, v126
	v_fmac_f32_e32 v88, v0, v87
	v_fmac_f32_e32 v53, v0, v52
	v_bfe_u32 v123, v119, 16, 1
	v_bfe_u32 v143, v127, 16, 1
	v_bfe_u32 v125, v88, 16, 1
	v_bfe_u32 v145, v53, 16, 1
	v_add3_u32 v123, v119, v123, s53
	v_add3_u32 v143, v127, v143, s53
	v_add3_u32 v125, v88, v125, s53
	v_add3_u32 v145, v53, v145, s53
	v_lshrrev_b32_e32 v123, 16, v123
	v_lshrrev_b32_e32 v143, 16, v143
	v_and_or_b32 v123, v125, s52, v123
	v_and_or_b32 v143, v145, s52, v143
	global_store_dword v22, v123, s[4:5]
	global_store_dword v22, v143, s[6:7]
	s_waitcnt vmcnt(63)
	s_waitcnt vmcnt(62)
	v_lshlrev_b32_e32 v118, 16, v89
	v_lshlrev_b32_e32 v126, 16, v54
	v_and_b32_e32 v89, 0xffff0000, v89
	v_and_b32_e32 v54, 0xffff0000, v54
	v_fmac_f32_e32 v118, v0, v119
	v_fmac_f32_e32 v126, v0, v127
	v_fmac_f32_e32 v89, v0, v88
	v_fmac_f32_e32 v54, v0, v53
	v_bfe_u32 v120, v118, 16, 1
	v_bfe_u32 v140, v126, 16, 1
	v_bfe_u32 v124, v89, 16, 1
	v_bfe_u32 v144, v54, 16, 1
	v_add3_u32 v120, v118, v120, s53
	v_add3_u32 v140, v126, v140, s53
	v_add3_u32 v124, v89, v124, s53
	v_add3_u32 v144, v54, v144, s53
	v_lshrrev_b32_e32 v120, 16, v120
	v_lshrrev_b32_e32 v140, 16, v140
	v_and_or_b32 v120, v124, s52, v120
	v_and_or_b32 v140, v144, s52, v140
	global_store_dword v23, v120, s[4:5]
	global_store_dword v23, v140, s[6:7]
	s_waitcnt vmcnt(63)
	s_waitcnt vmcnt(62)
	v_lshlrev_b32_e32 v119, 16, v90
	v_lshlrev_b32_e32 v127, 16, v55
	v_and_b32_e32 v90, 0xffff0000, v90
	v_and_b32_e32 v55, 0xffff0000, v55
	v_fmac_f32_e32 v119, v0, v118
	v_fmac_f32_e32 v127, v0, v126
	v_fmac_f32_e32 v90, v0, v89
	v_fmac_f32_e32 v55, v0, v54
	v_bfe_u32 v121, v119, 16, 1
	v_bfe_u32 v141, v127, 16, 1
	v_bfe_u32 v125, v90, 16, 1
	v_bfe_u32 v145, v55, 16, 1
	v_add3_u32 v121, v119, v121, s53
	v_add3_u32 v141, v127, v141, s53
	v_add3_u32 v125, v90, v125, s53
	v_add3_u32 v145, v55, v145, s53
	v_lshrrev_b32_e32 v121, 16, v121
	v_lshrrev_b32_e32 v141, 16, v141
	v_and_or_b32 v121, v125, s52, v121
	v_and_or_b32 v141, v145, s52, v141
	global_store_dword v24, v121, s[4:5]
	global_store_dword v24, v141, s[6:7]
	s_waitcnt vmcnt(63)
	s_waitcnt vmcnt(62)
	v_lshlrev_b32_e32 v118, 16, v91
	v_lshlrev_b32_e32 v126, 16, v56
	v_and_b32_e32 v91, 0xffff0000, v91
	v_and_b32_e32 v56, 0xffff0000, v56
	v_fmac_f32_e32 v118, v0, v119
	v_fmac_f32_e32 v126, v0, v127
	v_fmac_f32_e32 v91, v0, v90
	v_fmac_f32_e32 v56, v0, v55
	v_bfe_u32 v122, v118, 16, 1
	v_bfe_u32 v142, v126, 16, 1
	v_bfe_u32 v124, v91, 16, 1
	v_bfe_u32 v144, v56, 16, 1
	v_add3_u32 v122, v118, v122, s53
	v_add3_u32 v142, v126, v142, s53
	v_add3_u32 v124, v91, v124, s53
	v_add3_u32 v144, v56, v144, s53
	v_lshrrev_b32_e32 v122, 16, v122
	v_lshrrev_b32_e32 v142, 16, v142
	v_and_or_b32 v122, v124, s52, v122
	v_and_or_b32 v142, v144, s52, v142
	global_store_dword v25, v122, s[4:5]
	global_store_dword v25, v142, s[6:7]
	s_waitcnt vmcnt(63)
	s_waitcnt vmcnt(62)
	v_lshlrev_b32_e32 v119, 16, v92
	v_lshlrev_b32_e32 v127, 16, v57
	v_and_b32_e32 v92, 0xffff0000, v92
	v_and_b32_e32 v57, 0xffff0000, v57
	v_fmac_f32_e32 v119, v0, v118
	v_fmac_f32_e32 v127, v0, v126
	v_fmac_f32_e32 v92, v0, v91
	v_fmac_f32_e32 v57, v0, v56
	v_bfe_u32 v123, v119, 16, 1
	v_bfe_u32 v143, v127, 16, 1
	v_bfe_u32 v125, v92, 16, 1
	v_bfe_u32 v145, v57, 16, 1
	v_add3_u32 v123, v119, v123, s53
	v_add3_u32 v143, v127, v143, s53
	v_add3_u32 v125, v92, v125, s53
	v_add3_u32 v145, v57, v145, s53
	v_lshrrev_b32_e32 v123, 16, v123
	v_lshrrev_b32_e32 v143, 16, v143
	v_and_or_b32 v123, v125, s52, v123
	v_and_or_b32 v143, v145, s52, v143
	global_store_dword v26, v123, s[4:5]
	global_store_dword v26, v143, s[6:7]
	s_waitcnt vmcnt(63)
	s_waitcnt vmcnt(62)
	v_lshlrev_b32_e32 v118, 16, v93
	v_lshlrev_b32_e32 v126, 16, v58
	v_and_b32_e32 v93, 0xffff0000, v93
	v_and_b32_e32 v58, 0xffff0000, v58
	v_fmac_f32_e32 v118, v0, v119
	v_fmac_f32_e32 v126, v0, v127
	v_fmac_f32_e32 v93, v0, v92
	v_fmac_f32_e32 v58, v0, v57
	v_bfe_u32 v120, v118, 16, 1
	v_bfe_u32 v140, v126, 16, 1
	v_bfe_u32 v124, v93, 16, 1
	v_bfe_u32 v144, v58, 16, 1
	v_add3_u32 v120, v118, v120, s53
	v_add3_u32 v140, v126, v140, s53
	v_add3_u32 v124, v93, v124, s53
	v_add3_u32 v144, v58, v144, s53
	v_lshrrev_b32_e32 v120, 16, v120
	v_lshrrev_b32_e32 v140, 16, v140
	v_and_or_b32 v120, v124, s52, v120
	v_and_or_b32 v140, v144, s52, v140
	global_store_dword v27, v120, s[4:5]
	global_store_dword v27, v140, s[6:7]
	s_waitcnt vmcnt(63)
	s_waitcnt vmcnt(62)
	v_lshlrev_b32_e32 v119, 16, v94
	v_lshlrev_b32_e32 v127, 16, v59
	v_and_b32_e32 v94, 0xffff0000, v94
	v_and_b32_e32 v59, 0xffff0000, v59
	v_fmac_f32_e32 v119, v0, v118
	v_fmac_f32_e32 v127, v0, v126
	v_fmac_f32_e32 v94, v0, v93
	v_fmac_f32_e32 v59, v0, v58
	v_bfe_u32 v121, v119, 16, 1
	v_bfe_u32 v141, v127, 16, 1
	v_bfe_u32 v125, v94, 16, 1
	v_bfe_u32 v145, v59, 16, 1
	v_add3_u32 v121, v119, v121, s53
	v_add3_u32 v141, v127, v141, s53
	v_add3_u32 v125, v94, v125, s53
	v_add3_u32 v145, v59, v145, s53
	v_lshrrev_b32_e32 v121, 16, v121
	v_lshrrev_b32_e32 v141, 16, v141
	v_and_or_b32 v121, v125, s52, v121
	v_and_or_b32 v141, v145, s52, v141
	global_store_dword v28, v121, s[4:5]
	global_store_dword v28, v141, s[6:7]
	s_waitcnt vmcnt(63)
	s_waitcnt vmcnt(62)
	v_lshlrev_b32_e32 v118, 16, v95
	v_lshlrev_b32_e32 v126, 16, v60
	v_and_b32_e32 v95, 0xffff0000, v95
	v_and_b32_e32 v60, 0xffff0000, v60
	v_fmac_f32_e32 v118, v0, v119
	v_fmac_f32_e32 v126, v0, v127
	v_fmac_f32_e32 v95, v0, v94
	v_fmac_f32_e32 v60, v0, v59
	v_bfe_u32 v122, v118, 16, 1
	v_bfe_u32 v142, v126, 16, 1
	v_bfe_u32 v124, v95, 16, 1
	v_bfe_u32 v144, v60, 16, 1
	v_add3_u32 v122, v118, v122, s53
	v_add3_u32 v142, v126, v142, s53
	v_add3_u32 v124, v95, v124, s53
	v_add3_u32 v144, v60, v144, s53
	v_lshrrev_b32_e32 v122, 16, v122
	v_lshrrev_b32_e32 v142, 16, v142
	v_and_or_b32 v122, v124, s52, v122
	v_and_or_b32 v142, v144, s52, v142
	global_store_dword v29, v122, s[4:5]
	global_store_dword v29, v142, s[6:7]
	s_waitcnt vmcnt(63)
	s_waitcnt vmcnt(62)
	v_lshlrev_b32_e32 v119, 16, v96
	v_lshlrev_b32_e32 v127, 16, v61
	v_and_b32_e32 v96, 0xffff0000, v96
	v_and_b32_e32 v61, 0xffff0000, v61
	v_fmac_f32_e32 v119, v0, v118
	v_fmac_f32_e32 v127, v0, v126
	v_fmac_f32_e32 v96, v0, v95
	v_fmac_f32_e32 v61, v0, v60
	v_bfe_u32 v123, v119, 16, 1
	v_bfe_u32 v143, v127, 16, 1
	v_bfe_u32 v125, v96, 16, 1
	v_bfe_u32 v145, v61, 16, 1
	v_add3_u32 v123, v119, v123, s53
	v_add3_u32 v143, v127, v143, s53
	v_add3_u32 v125, v96, v125, s53
	v_add3_u32 v145, v61, v145, s53
	v_lshrrev_b32_e32 v123, 16, v123
	v_lshrrev_b32_e32 v143, 16, v143
	v_and_or_b32 v123, v125, s52, v123
	v_and_or_b32 v143, v145, s52, v143
	global_store_dword v30, v123, s[4:5]
	global_store_dword v30, v143, s[6:7]
	s_waitcnt vmcnt(63)
	s_waitcnt vmcnt(62)
	v_lshlrev_b32_e32 v118, 16, v97
	v_lshlrev_b32_e32 v126, 16, v62
	v_and_b32_e32 v97, 0xffff0000, v97
	v_and_b32_e32 v62, 0xffff0000, v62
	v_fmac_f32_e32 v118, v0, v119
	v_fmac_f32_e32 v126, v0, v127
	v_fmac_f32_e32 v97, v0, v96
	v_fmac_f32_e32 v62, v0, v61
	v_bfe_u32 v120, v118, 16, 1
	v_bfe_u32 v140, v126, 16, 1
	v_bfe_u32 v124, v97, 16, 1
	v_bfe_u32 v144, v62, 16, 1
	v_add3_u32 v120, v118, v120, s53
	v_add3_u32 v140, v126, v140, s53
	v_add3_u32 v124, v97, v124, s53
	v_add3_u32 v144, v62, v144, s53
	v_lshrrev_b32_e32 v120, 16, v120
	v_lshrrev_b32_e32 v140, 16, v140
	v_and_or_b32 v120, v124, s52, v120
	v_and_or_b32 v140, v144, s52, v140
	global_store_dword v31, v120, s[4:5]
	global_store_dword v31, v140, s[6:7]
	s_waitcnt vmcnt(63)
	s_waitcnt vmcnt(62)
	v_lshlrev_b32_e32 v119, 16, v98
	v_lshlrev_b32_e32 v127, 16, v63
	v_and_b32_e32 v98, 0xffff0000, v98
	v_and_b32_e32 v63, 0xffff0000, v63
	v_fmac_f32_e32 v119, v0, v118
	v_fmac_f32_e32 v127, v0, v126
	v_fmac_f32_e32 v98, v0, v97
	v_fmac_f32_e32 v63, v0, v62
	v_bfe_u32 v121, v119, 16, 1
	v_bfe_u32 v141, v127, 16, 1
	v_bfe_u32 v125, v98, 16, 1
	v_bfe_u32 v145, v63, 16, 1
	v_add3_u32 v121, v119, v121, s53
	v_add3_u32 v141, v127, v141, s53
	v_add3_u32 v125, v98, v125, s53
	v_add3_u32 v145, v63, v145, s53
	v_lshrrev_b32_e32 v121, 16, v121
	v_lshrrev_b32_e32 v141, 16, v141
	v_and_or_b32 v121, v125, s52, v121
	v_and_or_b32 v141, v145, s52, v141
	global_store_dword v32, v121, s[4:5]
	global_store_dword v32, v141, s[6:7]
	s_waitcnt vmcnt(63)
	s_waitcnt vmcnt(62)
	v_lshlrev_b32_e32 v118, 16, v99
	v_lshlrev_b32_e32 v126, 16, v113
	v_and_b32_e32 v99, 0xffff0000, v99
	v_and_b32_e32 v113, 0xffff0000, v113
	v_fmac_f32_e32 v118, v0, v119
	v_fmac_f32_e32 v126, v0, v127
	v_fmac_f32_e32 v99, v0, v98
	v_fmac_f32_e32 v113, v0, v63
	v_bfe_u32 v122, v118, 16, 1
	v_bfe_u32 v142, v126, 16, 1
	v_bfe_u32 v124, v99, 16, 1
	v_bfe_u32 v144, v113, 16, 1
	v_add3_u32 v122, v118, v122, s53
	v_add3_u32 v142, v126, v142, s53
	v_add3_u32 v124, v99, v124, s53
	v_add3_u32 v144, v113, v144, s53
	v_lshrrev_b32_e32 v122, 16, v122
	v_lshrrev_b32_e32 v142, 16, v142
	v_and_or_b32 v122, v124, s52, v122
	v_and_or_b32 v142, v144, s52, v142
	global_store_dword v33, v122, s[4:5]
	global_store_dword v33, v142, s[6:7]
	s_waitcnt vmcnt(63)
	s_waitcnt vmcnt(62)
	v_lshlrev_b32_e32 v119, 16, v100
	v_lshlrev_b32_e32 v127, 16, v114
	v_and_b32_e32 v100, 0xffff0000, v100
	v_and_b32_e32 v114, 0xffff0000, v114
	v_fmac_f32_e32 v119, v0, v118
	v_fmac_f32_e32 v127, v0, v126
	v_fmac_f32_e32 v100, v0, v99
	v_fmac_f32_e32 v114, v0, v113
	v_bfe_u32 v123, v119, 16, 1
	v_bfe_u32 v143, v127, 16, 1
	v_bfe_u32 v125, v100, 16, 1
	v_bfe_u32 v145, v114, 16, 1
	v_add3_u32 v123, v119, v123, s53
	v_add3_u32 v143, v127, v143, s53
	v_add3_u32 v125, v100, v125, s53
	v_add3_u32 v145, v114, v145, s53
	v_lshrrev_b32_e32 v123, 16, v123
	v_lshrrev_b32_e32 v143, 16, v143
	v_and_or_b32 v123, v125, s52, v123
	v_and_or_b32 v143, v145, s52, v143
	global_store_dword v34, v123, s[4:5]
	global_store_dword v34, v143, s[6:7]
	s_waitcnt vmcnt(63)
	s_waitcnt vmcnt(62)
	v_lshlrev_b32_e32 v118, 16, v101
	v_lshlrev_b32_e32 v126, 16, v115
	v_and_b32_e32 v101, 0xffff0000, v101
	v_and_b32_e32 v115, 0xffff0000, v115
	v_fmac_f32_e32 v118, v0, v119
	v_fmac_f32_e32 v126, v0, v127
	v_fmac_f32_e32 v101, v0, v100
	v_fmac_f32_e32 v115, v0, v114
	v_bfe_u32 v120, v118, 16, 1
	v_bfe_u32 v140, v126, 16, 1
	v_bfe_u32 v124, v101, 16, 1
	v_bfe_u32 v144, v115, 16, 1
	v_add3_u32 v120, v118, v120, s53
	v_add3_u32 v140, v126, v140, s53
	v_add3_u32 v124, v101, v124, s53
	v_add3_u32 v144, v115, v144, s53
	v_lshrrev_b32_e32 v120, 16, v120
	v_lshrrev_b32_e32 v140, 16, v140
	v_and_or_b32 v120, v124, s52, v120
	v_and_or_b32 v140, v144, s52, v140
	global_store_dword v35, v120, s[4:5]
	global_store_dword v35, v140, s[6:7]
	s_waitcnt vmcnt(63)
	s_waitcnt vmcnt(62)
	v_lshlrev_b32_e32 v119, 16, v102
	v_lshlrev_b32_e32 v127, 16, v116
	v_and_b32_e32 v102, 0xffff0000, v102
	v_and_b32_e32 v116, 0xffff0000, v116
	v_fmac_f32_e32 v119, v0, v118
	v_fmac_f32_e32 v127, v0, v126
	v_fmac_f32_e32 v102, v0, v101
	v_fmac_f32_e32 v116, v0, v115
	v_bfe_u32 v121, v119, 16, 1
	v_bfe_u32 v141, v127, 16, 1
	v_bfe_u32 v125, v102, 16, 1
	v_bfe_u32 v145, v116, 16, 1
	v_add3_u32 v121, v119, v121, s53
	v_add3_u32 v141, v127, v141, s53
	v_add3_u32 v125, v102, v125, s53
	v_add3_u32 v145, v116, v145, s53
	v_lshrrev_b32_e32 v121, 16, v121
	v_lshrrev_b32_e32 v141, 16, v141
	v_and_or_b32 v121, v125, s52, v121
	v_and_or_b32 v141, v145, s52, v141
	global_store_dword v36, v121, s[4:5]
	global_store_dword v36, v141, s[6:7]
	s_waitcnt vmcnt(63)
	s_waitcnt vmcnt(62)
	v_lshlrev_b32_e32 v118, 16, v103
	v_lshlrev_b32_e32 v126, 16, v117
	v_and_b32_e32 v103, 0xffff0000, v103
	v_and_b32_e32 v117, 0xffff0000, v117
	v_fmac_f32_e32 v118, v0, v119
	v_fmac_f32_e32 v126, v0, v127
	v_fmac_f32_e32 v103, v0, v102
	v_fmac_f32_e32 v117, v0, v116
	v_bfe_u32 v122, v118, 16, 1
	v_bfe_u32 v142, v126, 16, 1
	v_bfe_u32 v124, v103, 16, 1
	v_bfe_u32 v144, v117, 16, 1
	v_add3_u32 v122, v118, v122, s53
	v_add3_u32 v142, v126, v142, s53
	v_add3_u32 v124, v103, v124, s53
	v_add3_u32 v144, v117, v144, s53
	v_lshrrev_b32_e32 v122, 16, v122
	v_lshrrev_b32_e32 v142, 16, v142
	v_and_or_b32 v122, v124, s52, v122
	v_and_or_b32 v142, v144, s52, v142
	global_store_dword v37, v122, s[4:5]
	global_store_dword v37, v142, s[6:7]
	s_branch .LBB0_570
